# attention phase: one static s_setprio 1 for waves 4-7 (reset to 0 at the end of the phase)
# speedup vs baseline: 1.0029x; 1.0029x over previous
.LBB0_396:
	s_andn2_saveexec_b64 s[12:13], s[12:13]
	s_cbranch_execz .LBB0_474
	v_readfirstlane_b32 s98, v208
	s_nop 3
	s_lshr_b32 s98, s98, 8
	s_cmp_lg_u32 s98, 0
	s_cbranch_scc0 .Lmy_prio_skip
	s_setprio 1
.Lmy_prio_skip:
	s_add_u32 s54, s26, 0xa460000
	v_mov_b32_e32 v1, 0
	s_addc_u32 s55, s27, 0
	v_lshlrev_b32_e32 v0, 1, v4
	v_lshlrev_b32_e32 v4, 1, v3
	v_mov_b32_e32 v5, v1
	s_add_u32 s56, s26, 0xa440000
	v_mov_b32_e32 v187, v186
	v_lshl_add_u64 v[184:185], s[40:41], 0, v[0:1]
	v_lshl_add_u64 v[202:203], s[38:39], 0, v[4:5]
	v_lshl_add_u64 v[204:205], s[20:21], 0, v[0:1]
	s_mov_b32 s39, 0
	v_lshl_add_u32 v206, v2, 1, 0
	s_addc_u32 s57, s27, 0
	v_mov_b32_e32 v207, 0x3727c5ac
	s_mov_b32 s63, 0xf800000
	v_mov_b32_e32 v224, 0x260
	v_mov_b32_e32 v225, 0xff800000
	s_mov_b32 s64, 0
	s_branch .LBB0_400

.LBB0_474:
	s_or_b64 exec, exec, s[12:13]
	s_setprio 0
